# stack: older-half priority raise (attention + recurrence) + decode counted waits/s_load page table + bh-major prefill order
# baseline (speedup 1.0000x reference)
.LBB0_794:
	v_mov_b32_e32 v0, s89
	s_waitcnt lgkmcnt(0)
	s_barrier
	ds_read_b32 v0, v0
	s_mov_b64 s[0:1], -1
	s_waitcnt lgkmcnt(0)
	s_barrier
	v_readfirstlane_b32 s83, v0
	s_cmpk_gt_i32 s83, 0x507
	s_cbranch_scc1 .LBB0_787
	s_cmpk_gt_i32 s83, 0x4ff
	s_cbranch_scc1 .Latt_remap_done
	s_cmpk_gt_i32 s83, 0x2ff
	s_cbranch_scc1 .Latt_remap_late
	s_mul_hi_u32 s0, s83, 0xaaaaaaab
	s_lshr_b32 s0, s0, 1
	s_mul_i32 s1, s0, 3
	s_sub_i32 s1, s83, s1
	s_cmp_eq_u32 s1, 0
	s_cbranch_scc0 .Latt_remap_pre
	s_lshl_b32 s83, s0, 1
	s_or_b32 s83, s83, 1
	s_branch .Latt_remap_done
.Latt_remap_pre:
	s_sub_i32 s1, s83, s0
	s_add_i32 s1, s1, -1
	s_branch .Latt_remap_pi
.Latt_remap_late:
	s_add_i32 s1, s83, 0xffffff00
.Latt_remap_pi:
	s_cmpk_lt_u32 s1, 0x200
	s_cbranch_scc0 .Latt_remap_hi
	s_and_b32 s2, s1, 3
	s_lshr_b32 s3, s1, 2
	s_branch .Latt_remap_mk
.Latt_remap_hi:
	s_add_i32 s1, s1, 0xfffffe00
	s_lshr_b32 s2, s1, 8
	s_lshl_b32 s2, s2, 1
	s_and_b32 s3, s1, 1
	s_or_b32 s2, s2, s3
	s_add_i32 s2, s2, 4
	s_and_b32 s3, s1, 0xff
	s_lshr_b32 s3, s3, 1
.Latt_remap_mk:
	s_lshl_b32 s2, s2, 7
	s_or_b32 s1, s2, s3
	s_lshl_b32 s2, s1, 1
	s_add_i32 s3, s1, 0x100
	s_cmpk_lt_u32 s1, 0x100
	s_cselect_b32 s83, s2, s3
